# grid barrier: L1 invalidate issued just before the per-XCD ticket atomic so it also overlaps the ticket round trip
# baseline (speedup 1.0000x reference)
; __device__ __forceinline__ unsigned xb_add(unsigned* p, unsigned v) { return __hip_atomic_fetch_add(p, v, __ATOMIC_RELAXED, __HIP_MEMORY_SCOPE_AGENT); }
; __device__ __forceinline__ void xcd_barrier(const XcdBarrier& b) {
;     ...
;         const unsigned old = xb_add(&bar[XB_XSUB(b.x)], 1u);
.LBB0_568:
	buffer_inv sc1
	s_mov_b64 s[6:7], exec
	v_mbcnt_lo_u32_b32 v1, s6, 0
	v_mbcnt_hi_u32_b32 v1, s7, v1
	v_cmp_eq_u32_e32 vcc, 0, v1
	s_and_saveexec_b64 s[4:5], vcc
	s_cbranch_execz .LBB0_570
	s_bcnt1_i32_b64 s6, s[6:7]
	v_mov_b32_e32 v4, s6
	v_readlane_b32 s6, v252, 15
	v_readlane_b32 s7, v252, 16
	s_nop 4
	global_atomic_add v4, v3, v4, s[6:7] sc0
